# out-proj comp: second-half first B fragment read ahead into freed quad v[98:101], progressive lgkmcnt waits
# baseline (speedup 1.0000x reference)
.LBB0_80:
	ds_read_b128 v[114:117], v127 offset:16384
	ds_read_b128 v[118:121], v0
	ds_read_b128 v[166:169], v127 offset:18432
	ds_read_b128 v[170:173], v127 offset:20480
	ds_read_b128 v[174:177], v127 offset:22528
	ds_read_b128 v[238:241], v0 offset:2048
	ds_read_b128 v[242:245], v0 offset:4096
	ds_read_b128 v[246:249], v0 offset:6144
	s_andn2_b64 vcc, exec, s[38:39]
	s_waitcnt lgkmcnt(6)
	v_mfma_f32_16x16x32_bf16 v[78:81], v[114:117], v[118:121], v[78:81]
	ds_read_b128 v[230:233], v129 offset:16384
	ds_read_b128 v[234:237], v129 offset:22528
	ds_read_b128 v[90:93], v129 offset:18432
	ds_read_b128 v[94:97], v129 offset:20480
	ds_read_b128 v[98:101], v128
	s_waitcnt lgkmcnt(10)
	v_mfma_f32_16x16x32_bf16 v[74:77], v[166:169], v[118:121], v[74:77]
	s_waitcnt lgkmcnt(9)
	v_mfma_f32_16x16x32_bf16 v[70:73], v[170:173], v[118:121], v[70:73]
	s_waitcnt lgkmcnt(8)
	v_mfma_f32_16x16x32_bf16 v[66:69], v[174:177], v[118:121], v[66:69]
	s_waitcnt lgkmcnt(7)
	v_mfma_f32_16x16x32_bf16 v[62:65], v[114:117], v[238:241], v[62:65]
	v_mfma_f32_16x16x32_bf16 v[58:61], v[166:169], v[238:241], v[58:61]
	v_mfma_f32_16x16x32_bf16 v[54:57], v[170:173], v[238:241], v[54:57]
	v_mfma_f32_16x16x32_bf16 v[50:53], v[174:177], v[238:241], v[50:53]
	ds_read_b128 v[238:241], v128 offset:2048
	s_waitcnt lgkmcnt(7)
	v_mfma_f32_16x16x32_bf16 v[218:221], v[114:117], v[242:245], v[46:49]
	v_mfma_f32_16x16x32_bf16 v[222:225], v[166:169], v[242:245], v[42:45]
	v_mfma_f32_16x16x32_bf16 v[226:229], v[170:173], v[242:245], v[38:41]
	v_mfma_f32_16x16x32_bf16 v[118:121], v[174:177], v[242:245], v[34:37]
	ds_read_b128 v[242:245], v128 offset:4096
	s_waitcnt lgkmcnt(7)
	v_mfma_f32_16x16x32_bf16 v[114:117], v[114:117], v[246:249], v[30:33]
	v_mfma_f32_16x16x32_bf16 v[166:169], v[166:169], v[246:249], v[26:29]
	v_mfma_f32_16x16x32_bf16 v[170:173], v[170:173], v[246:249], v[22:25]
	v_mfma_f32_16x16x32_bf16 v[18:21], v[174:177], v[246:249], v[18:21]
	ds_read_b128 v[246:249], v128 offset:6144
	s_waitcnt lgkmcnt(2)
	v_mfma_f32_16x16x32_bf16 v[22:25], v[230:233], v[98:101], v[78:81]
	v_mfma_f32_16x16x32_bf16 v[26:29], v[90:93], v[98:101], v[74:77]
	v_mfma_f32_16x16x32_bf16 v[30:33], v[94:97], v[98:101], v[70:73]
	v_mfma_f32_16x16x32_bf16 v[34:37], v[234:237], v[98:101], v[66:69]
	v_mfma_f32_16x16x32_bf16 v[38:41], v[230:233], v[238:241], v[62:65]
	v_mfma_f32_16x16x32_bf16 v[42:45], v[90:93], v[238:241], v[58:61]
	v_mfma_f32_16x16x32_bf16 v[46:49], v[94:97], v[238:241], v[54:57]
	v_mfma_f32_16x16x32_bf16 v[50:53], v[234:237], v[238:241], v[50:53]
	s_waitcnt lgkmcnt(1)
	v_mfma_f32_16x16x32_bf16 v[54:57], v[230:233], v[242:245], v[218:221]
	v_mfma_f32_16x16x32_bf16 v[58:61], v[90:93], v[242:245], v[222:225]
	v_mfma_f32_16x16x32_bf16 v[62:65], v[94:97], v[242:245], v[226:229]
	v_mfma_f32_16x16x32_bf16 v[66:69], v[234:237], v[242:245], v[118:121]
	s_waitcnt lgkmcnt(0)
	v_mfma_f32_16x16x32_bf16 v[70:73], v[230:233], v[246:249], v[114:117]
	v_mfma_f32_16x16x32_bf16 v[74:77], v[90:93], v[246:249], v[166:169]
	v_mfma_f32_16x16x32_bf16 v[78:81], v[94:97], v[246:249], v[170:173]
	v_mfma_f32_16x16x32_bf16 v[18:21], v[234:237], v[246:249], v[18:21]
	s_cbranch_vccnz .LBB0_82
	s_waitcnt vmcnt(0)
	ds_write_b16 v130, v2 offset:36864
	ds_write_b16_d16_hi v130, v2 offset:36992
	ds_write_b16 v131, v3 offset:36864
	ds_write_b16_d16_hi v132, v3 offset:36864
	ds_write_b16 v133, v4 offset:36864
	ds_write_b16_d16_hi v134, v4 offset:36864
	ds_write_b16 v135, v5 offset:36864
	ds_write_b16_d16_hi v136, v5 offset:36864
	ds_write_b16 v137, v6 offset:36864
	ds_write_b16_d16_hi v137, v6 offset:36992
	ds_write_b16 v138, v7 offset:36864
	ds_write_b16_d16_hi v139, v7 offset:36864
	ds_write_b16 v140, v8 offset:36864
	ds_write_b16_d16_hi v141, v8 offset:36864
	ds_write_b16 v142, v9 offset:36864
	ds_write_b16_d16_hi v143, v9 offset:36864
	ds_write_b16 v144, v10 offset:36864
	ds_write_b16_d16_hi v144, v10 offset:36992
	ds_write_b16 v145, v11 offset:36864
	ds_write_b16_d16_hi v154, v11 offset:36864
	ds_write_b16 v155, v12 offset:36864
	ds_write_b16_d16_hi v156, v12 offset:36864
	ds_write_b16 v157, v13 offset:36864
	ds_write_b16_d16_hi v158, v13 offset:36864
	ds_write_b16 v159, v14 offset:36864
	ds_write_b16_d16_hi v159, v14 offset:36992
	ds_write_b16 v160, v15 offset:36864
	ds_write_b16_d16_hi v161, v15 offset:36864
	ds_write_b16 v162, v16 offset:36864
	ds_write_b16_d16_hi v163, v16 offset:36864
	ds_write_b16 v164, v17 offset:36864
	ds_write_b16_d16_hi v165, v17 offset:36864

.LBB0_87:
	ds_read_b128 v[106:109], v127 offset:53248
	ds_read_b128 v[110:113], v0 offset:36864
	ds_read_b128 v[114:117], v127 offset:55296
	ds_read_b128 v[118:121], v127 offset:57344
	ds_read_b128 v[166:169], v127 offset:59392
	ds_read_b128 v[238:241], v0 offset:38912
	ds_read_b128 v[242:245], v0 offset:40960
	ds_read_b128 v[246:249], v0 offset:43008
	s_andn2_b64 vcc, exec, s[40:41]
	s_waitcnt lgkmcnt(6)
	v_mfma_f32_16x16x32_bf16 v[22:25], v[106:109], v[110:113], v[22:25]
	ds_read_b128 v[222:225], v129 offset:53248
	ds_read_b128 v[226:229], v129 offset:59392
	ds_read_b128 v[90:93], v129 offset:55296
	ds_read_b128 v[94:97], v129 offset:57344
	ds_read_b128 v[98:101], v128 offset:36864
	s_waitcnt lgkmcnt(10)
	v_mfma_f32_16x16x32_bf16 v[26:29], v[114:117], v[110:113], v[26:29]
	s_waitcnt lgkmcnt(9)
	v_mfma_f32_16x16x32_bf16 v[30:33], v[118:121], v[110:113], v[30:33]
	s_waitcnt lgkmcnt(8)
	v_mfma_f32_16x16x32_bf16 v[34:37], v[166:169], v[110:113], v[34:37]
	s_waitcnt lgkmcnt(7)
	v_mfma_f32_16x16x32_bf16 v[38:41], v[106:109], v[238:241], v[38:41]
	v_mfma_f32_16x16x32_bf16 v[42:45], v[114:117], v[238:241], v[42:45]
	v_mfma_f32_16x16x32_bf16 v[46:49], v[118:121], v[238:241], v[46:49]
	v_mfma_f32_16x16x32_bf16 v[50:53], v[166:169], v[238:241], v[50:53]
	ds_read_b128 v[238:241], v128 offset:38912
	s_waitcnt lgkmcnt(7)
	v_mfma_f32_16x16x32_bf16 v[170:173], v[106:109], v[242:245], v[54:57]
	v_mfma_f32_16x16x32_bf16 v[174:177], v[114:117], v[242:245], v[58:61]
	v_mfma_f32_16x16x32_bf16 v[218:221], v[118:121], v[242:245], v[62:65]
	v_mfma_f32_16x16x32_bf16 v[110:113], v[166:169], v[242:245], v[66:69]
	ds_read_b128 v[242:245], v128 offset:40960
	s_waitcnt lgkmcnt(7)
	v_mfma_f32_16x16x32_bf16 v[106:109], v[106:109], v[246:249], v[70:73]
	v_mfma_f32_16x16x32_bf16 v[114:117], v[114:117], v[246:249], v[74:77]
	v_mfma_f32_16x16x32_bf16 v[118:121], v[118:121], v[246:249], v[78:81]
	v_mfma_f32_16x16x32_bf16 v[18:21], v[166:169], v[246:249], v[18:21]
	ds_read_b128 v[246:249], v128 offset:43008
	s_waitcnt lgkmcnt(2)
	v_mfma_f32_16x16x32_bf16 v[78:81], v[222:225], v[98:101], v[22:25]
	v_mfma_f32_16x16x32_bf16 v[74:77], v[90:93], v[98:101], v[26:29]
	v_mfma_f32_16x16x32_bf16 v[70:73], v[94:97], v[98:101], v[30:33]
	v_mfma_f32_16x16x32_bf16 v[66:69], v[226:229], v[98:101], v[34:37]
	v_mfma_f32_16x16x32_bf16 v[62:65], v[222:225], v[238:241], v[38:41]
	v_mfma_f32_16x16x32_bf16 v[58:61], v[90:93], v[238:241], v[42:45]
	v_mfma_f32_16x16x32_bf16 v[54:57], v[94:97], v[238:241], v[46:49]
	v_mfma_f32_16x16x32_bf16 v[50:53], v[226:229], v[238:241], v[50:53]
	s_waitcnt lgkmcnt(1)
	v_mfma_f32_16x16x32_bf16 v[34:37], v[226:229], v[242:245], v[110:113]
	v_mfma_f32_16x16x32_bf16 v[46:49], v[222:225], v[242:245], v[170:173]
	v_mfma_f32_16x16x32_bf16 v[42:45], v[90:93], v[242:245], v[174:177]
	v_mfma_f32_16x16x32_bf16 v[38:41], v[94:97], v[242:245], v[218:221]
	s_waitcnt lgkmcnt(0)
	v_mfma_f32_16x16x32_bf16 v[30:33], v[222:225], v[246:249], v[106:109]
	v_mfma_f32_16x16x32_bf16 v[26:29], v[90:93], v[246:249], v[114:117]
	v_mfma_f32_16x16x32_bf16 v[22:25], v[94:97], v[246:249], v[118:121]
	v_mfma_f32_16x16x32_bf16 v[18:21], v[226:229], v[246:249], v[18:21]
	s_cbranch_vccnz .LBB0_75
	s_waitcnt vmcnt(0)
	ds_write_b16 v130, v2
	ds_write_b16_d16_hi v130, v2 offset:128
	ds_write_b16 v131, v3
	ds_write_b16_d16_hi v132, v3
	ds_write_b16 v133, v4
	ds_write_b16_d16_hi v134, v4
	ds_write_b16 v135, v5
	ds_write_b16_d16_hi v136, v5
	ds_write_b16 v137, v6
	ds_write_b16_d16_hi v137, v6 offset:128
	ds_write_b16 v138, v7
	ds_write_b16_d16_hi v139, v7
	ds_write_b16 v140, v8
	ds_write_b16_d16_hi v141, v8
	ds_write_b16 v142, v9
	ds_write_b16_d16_hi v143, v9
	ds_write_b16 v144, v10
	ds_write_b16_d16_hi v144, v10 offset:128
	ds_write_b16 v145, v11
	ds_write_b16_d16_hi v154, v11
	ds_write_b16 v155, v12
	ds_write_b16_d16_hi v156, v12
	ds_write_b16 v157, v13
	ds_write_b16_d16_hi v158, v13
	ds_write_b16 v159, v14
	ds_write_b16_d16_hi v159, v14 offset:128
	ds_write_b16 v160, v15
	ds_write_b16_d16_hi v161, v15
	ds_write_b16 v162, v16
	ds_write_b16_d16_hi v163, v16
	ds_write_b16 v164, v17
	ds_write_b16_d16_hi v165, v17
	s_branch .LBB0_75
